# cache-policy: nt (streaming) hint on the residual-tile LOADS only of the G2/G4 main epilogues, stores unchanged, so the freshly written residual rows stay cached for the following RMS phase
# baseline (speedup 1.0000x reference)
.LBB0_538:
	v_mov_b32_e32 v140, v142
	v_lshl_or_b32 v146, s68, 8, v144
	v_lshl_add_u32 v140, s69, 8, v140
	v_lshl_add_u32 v140, v140, 10, v146
	v_lshlrev_b32_e32 v140, 2, v140
	s_mov_b64 s[8:9], 0xb0000
	s_mov_b64 s[50:51], -1
	s_and_b64 vcc, exec, s[38:39]
	v_add_u32_e32 v141, 0x10000, v140
	v_add_u32_e32 v186, 0x20000, v140
	v_add_u32_e32 v187, 0x30000, v140
	v_add_u32_e32 v202, 0x80000, v140
	v_add_u32_e32 v203, 0x90000, v140
	v_add_u32_e32 v248, 0xa0000, v140
	v_add_u32_e32 v249, 0xb0000, v140
	global_load_dwordx4 v[146:149], v140, s[42:43] nt
	global_load_dwordx4 v[150:153], v140, s[42:43] offset:16 nt
	global_load_dwordx4 v[154:157], v140, s[42:43] offset:512 nt
	global_load_dwordx4 v[158:161], v140, s[42:43] offset:528 nt
	global_load_dwordx4 v[162:165], v141, s[42:43] nt
	global_load_dwordx4 v[166:169], v141, s[42:43] offset:16 nt
	global_load_dwordx4 v[170:173], v141, s[42:43] offset:512 nt
	global_load_dwordx4 v[174:177], v141, s[42:43] offset:528 nt
	global_load_dwordx4 v[178:181], v186, s[42:43] nt
	global_load_dwordx4 v[182:185], v186, s[42:43] offset:16 nt
	global_load_dwordx4 v[224:227], v186, s[42:43] offset:512 nt
	global_load_dwordx4 v[228:231], v186, s[42:43] offset:528 nt
	global_load_dwordx4 v[232:235], v187, s[42:43] nt
	global_load_dwordx4 v[236:239], v187, s[42:43] offset:16 nt
	global_load_dwordx4 v[240:243], v187, s[42:43] offset:512 nt
	global_load_dwordx4 v[244:247], v187, s[42:43] offset:528 nt
	s_waitcnt vmcnt(12)
	v_pk_fma_f32 v[126:127], v[126:127], 0.5, v[146:147] op_sel_hi:[1,0,1]
	v_pk_fma_f32 v[128:129], v[128:129], 0.5, v[148:149] op_sel_hi:[1,0,1]
	v_pk_fma_f32 v[122:123], v[122:123], 0.5, v[150:151] op_sel_hi:[1,0,1]
	v_pk_fma_f32 v[124:125], v[124:125], 0.5, v[152:153] op_sel_hi:[1,0,1]
	v_pk_fma_f32 v[118:119], v[118:119], 0.5, v[154:155] op_sel_hi:[1,0,1]
	v_pk_fma_f32 v[120:121], v[120:121], 0.5, v[156:157] op_sel_hi:[1,0,1]
	v_pk_fma_f32 v[114:115], v[114:115], 0.5, v[158:159] op_sel_hi:[1,0,1]
	v_pk_fma_f32 v[116:117], v[116:117], 0.5, v[160:161] op_sel_hi:[1,0,1]
	global_store_dwordx4 v140, v[126:129], s[24:25]
	global_store_dwordx4 v140, v[122:125], s[24:25] offset:16
	global_store_dwordx4 v140, v[118:121], s[24:25] offset:512
	global_store_dwordx4 v140, v[114:117], s[24:25] offset:528
	global_load_dwordx4 v[146:149], v202, s[42:43] nt
	global_load_dwordx4 v[150:153], v202, s[42:43] offset:16 nt
	global_load_dwordx4 v[154:157], v202, s[42:43] offset:512 nt
	global_load_dwordx4 v[158:161], v202, s[42:43] offset:528 nt
	s_waitcnt vmcnt(16)
	v_pk_fma_f32 v[110:111], v[110:111], 0.5, v[162:163] op_sel_hi:[1,0,1]
	v_pk_fma_f32 v[112:113], v[112:113], 0.5, v[164:165] op_sel_hi:[1,0,1]
	v_pk_fma_f32 v[106:107], v[106:107], 0.5, v[166:167] op_sel_hi:[1,0,1]
	v_pk_fma_f32 v[108:109], v[108:109], 0.5, v[168:169] op_sel_hi:[1,0,1]
	v_pk_fma_f32 v[102:103], v[102:103], 0.5, v[170:171] op_sel_hi:[1,0,1]
	v_pk_fma_f32 v[104:105], v[104:105], 0.5, v[172:173] op_sel_hi:[1,0,1]
	v_pk_fma_f32 v[98:99], v[98:99], 0.5, v[174:175] op_sel_hi:[1,0,1]
	v_pk_fma_f32 v[100:101], v[100:101], 0.5, v[176:177] op_sel_hi:[1,0,1]
	global_store_dwordx4 v141, v[110:113], s[24:25]
	global_store_dwordx4 v141, v[106:109], s[24:25] offset:16
	global_store_dwordx4 v141, v[102:105], s[24:25] offset:512
	global_store_dwordx4 v141, v[98:101], s[24:25] offset:528
	global_load_dwordx4 v[162:165], v203, s[42:43] nt
	global_load_dwordx4 v[166:169], v203, s[42:43] offset:16 nt
	global_load_dwordx4 v[170:173], v203, s[42:43] offset:512 nt
	global_load_dwordx4 v[174:177], v203, s[42:43] offset:528 nt
	s_waitcnt vmcnt(20)
	v_pk_fma_f32 v[94:95], v[94:95], 0.5, v[178:179] op_sel_hi:[1,0,1]
	v_pk_fma_f32 v[96:97], v[96:97], 0.5, v[180:181] op_sel_hi:[1,0,1]
	v_pk_fma_f32 v[90:91], v[90:91], 0.5, v[182:183] op_sel_hi:[1,0,1]
	v_pk_fma_f32 v[92:93], v[92:93], 0.5, v[184:185] op_sel_hi:[1,0,1]
	v_pk_fma_f32 v[86:87], v[86:87], 0.5, v[224:225] op_sel_hi:[1,0,1]
	v_pk_fma_f32 v[88:89], v[88:89], 0.5, v[226:227] op_sel_hi:[1,0,1]
	v_pk_fma_f32 v[82:83], v[82:83], 0.5, v[228:229] op_sel_hi:[1,0,1]
	v_pk_fma_f32 v[84:85], v[84:85], 0.5, v[230:231] op_sel_hi:[1,0,1]
	global_store_dwordx4 v186, v[94:97], s[24:25]
	global_store_dwordx4 v186, v[90:93], s[24:25] offset:16
	global_store_dwordx4 v186, v[86:89], s[24:25] offset:512
	global_store_dwordx4 v186, v[82:85], s[24:25] offset:528
	global_load_dwordx4 v[178:181], v248, s[42:43] nt
	global_load_dwordx4 v[182:185], v248, s[42:43] offset:16 nt
	global_load_dwordx4 v[224:227], v248, s[42:43] offset:512 nt
	global_load_dwordx4 v[228:231], v248, s[42:43] offset:528 nt
	s_waitcnt vmcnt(24)
	v_pk_fma_f32 v[78:79], v[78:79], 0.5, v[232:233] op_sel_hi:[1,0,1]
	v_pk_fma_f32 v[80:81], v[80:81], 0.5, v[234:235] op_sel_hi:[1,0,1]
	v_pk_fma_f32 v[74:75], v[74:75], 0.5, v[236:237] op_sel_hi:[1,0,1]
	v_pk_fma_f32 v[76:77], v[76:77], 0.5, v[238:239] op_sel_hi:[1,0,1]
	v_pk_fma_f32 v[70:71], v[70:71], 0.5, v[240:241] op_sel_hi:[1,0,1]
	v_pk_fma_f32 v[72:73], v[72:73], 0.5, v[242:243] op_sel_hi:[1,0,1]
	v_pk_fma_f32 v[66:67], v[66:67], 0.5, v[244:245] op_sel_hi:[1,0,1]
	v_pk_fma_f32 v[68:69], v[68:69], 0.5, v[246:247] op_sel_hi:[1,0,1]
	global_store_dwordx4 v187, v[78:81], s[24:25]
	global_store_dwordx4 v187, v[74:77], s[24:25] offset:16
	global_store_dwordx4 v187, v[70:73], s[24:25] offset:512
	global_store_dwordx4 v187, v[66:69], s[24:25] offset:528
	global_load_dwordx4 v[232:235], v249, s[42:43] nt
	global_load_dwordx4 v[236:239], v249, s[42:43] offset:16 nt
	global_load_dwordx4 v[240:243], v249, s[42:43] offset:512 nt
	global_load_dwordx4 v[244:247], v249, s[42:43] offset:528 nt
	s_waitcnt vmcnt(24)
	v_pk_fma_f32 v[62:63], v[62:63], 0.5, v[146:147] op_sel_hi:[1,0,1]
	v_pk_fma_f32 v[64:65], v[64:65], 0.5, v[148:149] op_sel_hi:[1,0,1]
	v_pk_fma_f32 v[58:59], v[58:59], 0.5, v[150:151] op_sel_hi:[1,0,1]
	v_pk_fma_f32 v[60:61], v[60:61], 0.5, v[152:153] op_sel_hi:[1,0,1]
	v_pk_fma_f32 v[54:55], v[54:55], 0.5, v[154:155] op_sel_hi:[1,0,1]
	v_pk_fma_f32 v[56:57], v[56:57], 0.5, v[156:157] op_sel_hi:[1,0,1]
	v_pk_fma_f32 v[50:51], v[50:51], 0.5, v[158:159] op_sel_hi:[1,0,1]
	v_pk_fma_f32 v[52:53], v[52:53], 0.5, v[160:161] op_sel_hi:[1,0,1]
	global_store_dwordx4 v202, v[62:65], s[24:25]
	global_store_dwordx4 v202, v[58:61], s[24:25] offset:16
	global_store_dwordx4 v202, v[54:57], s[24:25] offset:512
	global_store_dwordx4 v202, v[50:53], s[24:25] offset:528
	s_waitcnt vmcnt(20)
	v_pk_fma_f32 v[46:47], v[46:47], 0.5, v[162:163] op_sel_hi:[1,0,1]
	v_pk_fma_f32 v[48:49], v[48:49], 0.5, v[164:165] op_sel_hi:[1,0,1]
	v_pk_fma_f32 v[42:43], v[42:43], 0.5, v[166:167] op_sel_hi:[1,0,1]
	v_pk_fma_f32 v[44:45], v[44:45], 0.5, v[168:169] op_sel_hi:[1,0,1]
	v_pk_fma_f32 v[38:39], v[38:39], 0.5, v[170:171] op_sel_hi:[1,0,1]
	v_pk_fma_f32 v[40:41], v[40:41], 0.5, v[172:173] op_sel_hi:[1,0,1]
	v_pk_fma_f32 v[34:35], v[34:35], 0.5, v[174:175] op_sel_hi:[1,0,1]
	v_pk_fma_f32 v[36:37], v[36:37], 0.5, v[176:177] op_sel_hi:[1,0,1]
	global_store_dwordx4 v203, v[46:49], s[24:25]
	global_store_dwordx4 v203, v[42:45], s[24:25] offset:16
	global_store_dwordx4 v203, v[38:41], s[24:25] offset:512
	global_store_dwordx4 v203, v[34:37], s[24:25] offset:528
	s_waitcnt vmcnt(16)
	v_pk_fma_f32 v[30:31], v[30:31], 0.5, v[178:179] op_sel_hi:[1,0,1]
	v_pk_fma_f32 v[32:33], v[32:33], 0.5, v[180:181] op_sel_hi:[1,0,1]
	v_pk_fma_f32 v[26:27], v[26:27], 0.5, v[182:183] op_sel_hi:[1,0,1]
	v_pk_fma_f32 v[28:29], v[28:29], 0.5, v[184:185] op_sel_hi:[1,0,1]
	v_pk_fma_f32 v[22:23], v[22:23], 0.5, v[224:225] op_sel_hi:[1,0,1]
	v_pk_fma_f32 v[24:25], v[24:25], 0.5, v[226:227] op_sel_hi:[1,0,1]
	v_pk_fma_f32 v[18:19], v[18:19], 0.5, v[228:229] op_sel_hi:[1,0,1]
	v_pk_fma_f32 v[20:21], v[20:21], 0.5, v[230:231] op_sel_hi:[1,0,1]
	global_store_dwordx4 v248, v[30:33], s[24:25]
	global_store_dwordx4 v248, v[26:29], s[24:25] offset:16
	global_store_dwordx4 v248, v[22:25], s[24:25] offset:512
	global_store_dwordx4 v248, v[18:21], s[24:25] offset:528
	s_waitcnt vmcnt(12)
	v_pk_fma_f32 v[14:15], v[14:15], 0.5, v[232:233] op_sel_hi:[1,0,1]
	v_pk_fma_f32 v[16:17], v[16:17], 0.5, v[234:235] op_sel_hi:[1,0,1]
	v_pk_fma_f32 v[10:11], v[10:11], 0.5, v[236:237] op_sel_hi:[1,0,1]
	v_pk_fma_f32 v[12:13], v[12:13], 0.5, v[238:239] op_sel_hi:[1,0,1]
	v_pk_fma_f32 v[6:7], v[6:7], 0.5, v[240:241] op_sel_hi:[1,0,1]
	v_pk_fma_f32 v[8:9], v[8:9], 0.5, v[242:243] op_sel_hi:[1,0,1]
	v_pk_fma_f32 v[2:3], v[2:3], 0.5, v[244:245] op_sel_hi:[1,0,1]
	v_pk_fma_f32 v[4:5], v[4:5], 0.5, v[246:247] op_sel_hi:[1,0,1]
	global_store_dwordx4 v249, v[14:17], s[24:25]
	global_store_dwordx4 v249, v[10:13], s[24:25] offset:16
	global_store_dwordx4 v249, v[6:9], s[24:25] offset:512
	global_store_dwordx4 v249, v[2:5], s[24:25] offset:528
	s_cbranch_vccnz .LBB0_523
	s_andn2_b64 vcc, exec, s[44:45]
	s_cbranch_vccnz .LBB0_522
	s_barrier
	s_branch .LBB0_522

.LBB0_1541:
	v_mov_b32_e32 v140, v142
	v_lshl_or_b32 v146, s65, 8, v144
	v_lshl_add_u32 v140, s66, 8, v140
	v_lshl_add_u32 v140, v140, 10, v146
	v_lshlrev_b32_e32 v140, 2, v140
	s_mov_b64 s[8:9], 0xb0000
	s_mov_b64 s[52:53], -1
	s_andn2_b64 vcc, exec, s[38:39]
	v_add_u32_e32 v141, 0x10000, v140
	v_add_u32_e32 v186, 0x20000, v140
	v_add_u32_e32 v187, 0x30000, v140
	v_add_u32_e32 v202, 0x80000, v140
	v_add_u32_e32 v203, 0x90000, v140
	v_add_u32_e32 v248, 0xa0000, v140
	v_add_u32_e32 v249, 0xb0000, v140
	global_load_dwordx4 v[146:149], v140, s[24:25] nt
	global_load_dwordx4 v[150:153], v140, s[24:25] offset:16 nt
	global_load_dwordx4 v[154:157], v140, s[24:25] offset:512 nt
	global_load_dwordx4 v[158:161], v140, s[24:25] offset:528 nt
	global_load_dwordx4 v[162:165], v141, s[24:25] nt
	global_load_dwordx4 v[166:169], v141, s[24:25] offset:16 nt
	global_load_dwordx4 v[170:173], v141, s[24:25] offset:512 nt
	global_load_dwordx4 v[174:177], v141, s[24:25] offset:528 nt
	global_load_dwordx4 v[178:181], v186, s[24:25] nt
	global_load_dwordx4 v[182:185], v186, s[24:25] offset:16 nt
	global_load_dwordx4 v[224:227], v186, s[24:25] offset:512 nt
	global_load_dwordx4 v[228:231], v186, s[24:25] offset:528 nt
	global_load_dwordx4 v[232:235], v187, s[24:25] nt
	global_load_dwordx4 v[236:239], v187, s[24:25] offset:16 nt
	global_load_dwordx4 v[240:243], v187, s[24:25] offset:512 nt
	global_load_dwordx4 v[244:247], v187, s[24:25] offset:528 nt
	s_waitcnt vmcnt(12)
	v_pk_add_f32 v[126:127], v[126:127], v[146:147]
	v_pk_add_f32 v[128:129], v[128:129], v[148:149]
	v_pk_add_f32 v[122:123], v[122:123], v[150:151]
	v_pk_add_f32 v[124:125], v[124:125], v[152:153]
	v_pk_add_f32 v[118:119], v[118:119], v[154:155]
	v_pk_add_f32 v[120:121], v[120:121], v[156:157]
	v_pk_add_f32 v[114:115], v[114:115], v[158:159]
	v_pk_add_f32 v[116:117], v[116:117], v[160:161]
	global_store_dwordx4 v140, v[126:129], s[24:25]
	global_store_dwordx4 v140, v[122:125], s[24:25] offset:16
	global_store_dwordx4 v140, v[118:121], s[24:25] offset:512
	global_store_dwordx4 v140, v[114:117], s[24:25] offset:528
	global_load_dwordx4 v[146:149], v202, s[24:25] nt
	global_load_dwordx4 v[150:153], v202, s[24:25] offset:16 nt
	global_load_dwordx4 v[154:157], v202, s[24:25] offset:512 nt
	global_load_dwordx4 v[158:161], v202, s[24:25] offset:528 nt
	s_waitcnt vmcnt(16)
	v_pk_add_f32 v[110:111], v[110:111], v[162:163]
	v_pk_add_f32 v[112:113], v[112:113], v[164:165]
	v_pk_add_f32 v[106:107], v[106:107], v[166:167]
	v_pk_add_f32 v[108:109], v[108:109], v[168:169]
	v_pk_add_f32 v[94:95], v[94:95], v[170:171]
	v_pk_add_f32 v[96:97], v[96:97], v[172:173]
	v_pk_add_f32 v[90:91], v[90:91], v[174:175]
	v_pk_add_f32 v[92:93], v[92:93], v[176:177]
	global_store_dwordx4 v141, v[110:113], s[24:25]
	global_store_dwordx4 v141, v[106:109], s[24:25] offset:16
	global_store_dwordx4 v141, v[94:97], s[24:25] offset:512
	global_store_dwordx4 v141, v[90:93], s[24:25] offset:528
	global_load_dwordx4 v[162:165], v203, s[24:25] nt
	global_load_dwordx4 v[166:169], v203, s[24:25] offset:16 nt
	global_load_dwordx4 v[170:173], v203, s[24:25] offset:512 nt
	global_load_dwordx4 v[174:177], v203, s[24:25] offset:528 nt
	s_waitcnt vmcnt(20)
	v_pk_add_f32 v[102:103], v[102:103], v[178:179]
	v_pk_add_f32 v[104:105], v[104:105], v[180:181]
	v_pk_add_f32 v[98:99], v[98:99], v[182:183]
	v_pk_add_f32 v[100:101], v[100:101], v[184:185]
	v_pk_add_f32 v[86:87], v[86:87], v[224:225]
	v_pk_add_f32 v[88:89], v[88:89], v[226:227]
	v_pk_add_f32 v[82:83], v[82:83], v[228:229]
	v_pk_add_f32 v[84:85], v[84:85], v[230:231]
	global_store_dwordx4 v186, v[102:105], s[24:25]
	global_store_dwordx4 v186, v[98:101], s[24:25] offset:16
	global_store_dwordx4 v186, v[86:89], s[24:25] offset:512
	global_store_dwordx4 v186, v[82:85], s[24:25] offset:528
	global_load_dwordx4 v[178:181], v248, s[24:25] nt
	global_load_dwordx4 v[182:185], v248, s[24:25] offset:16 nt
	global_load_dwordx4 v[224:227], v248, s[24:25] offset:512 nt
	global_load_dwordx4 v[228:231], v248, s[24:25] offset:528 nt
	s_waitcnt vmcnt(24)
	v_pk_add_f32 v[78:79], v[78:79], v[232:233]
	v_pk_add_f32 v[80:81], v[80:81], v[234:235]
	v_pk_add_f32 v[74:75], v[74:75], v[236:237]
	v_pk_add_f32 v[76:77], v[76:77], v[238:239]
	v_pk_add_f32 v[70:71], v[70:71], v[240:241]
	v_pk_add_f32 v[72:73], v[72:73], v[242:243]
	v_pk_add_f32 v[66:67], v[66:67], v[244:245]
	v_pk_add_f32 v[68:69], v[68:69], v[246:247]
	global_store_dwordx4 v187, v[78:81], s[24:25]
	global_store_dwordx4 v187, v[74:77], s[24:25] offset:16
	global_store_dwordx4 v187, v[70:73], s[24:25] offset:512
	global_store_dwordx4 v187, v[66:69], s[24:25] offset:528
	global_load_dwordx4 v[232:235], v249, s[24:25] nt
	global_load_dwordx4 v[236:239], v249, s[24:25] offset:16 nt
	global_load_dwordx4 v[240:243], v249, s[24:25] offset:512 nt
	global_load_dwordx4 v[244:247], v249, s[24:25] offset:528 nt
	s_waitcnt vmcnt(24)
	v_pk_add_f32 v[62:63], v[62:63], v[146:147]
	v_pk_add_f32 v[64:65], v[64:65], v[148:149]
	v_pk_add_f32 v[58:59], v[58:59], v[150:151]
	v_pk_add_f32 v[60:61], v[60:61], v[152:153]
	v_pk_add_f32 v[54:55], v[54:55], v[154:155]
	v_pk_add_f32 v[56:57], v[56:57], v[156:157]
	v_pk_add_f32 v[50:51], v[50:51], v[158:159]
	v_pk_add_f32 v[52:53], v[52:53], v[160:161]
	global_store_dwordx4 v202, v[62:65], s[24:25]
	global_store_dwordx4 v202, v[58:61], s[24:25] offset:16
	global_store_dwordx4 v202, v[54:57], s[24:25] offset:512
	global_store_dwordx4 v202, v[50:53], s[24:25] offset:528
	s_waitcnt vmcnt(20)
	v_pk_add_f32 v[46:47], v[46:47], v[162:163]
	v_pk_add_f32 v[48:49], v[48:49], v[164:165]
	v_pk_add_f32 v[42:43], v[42:43], v[166:167]
	v_pk_add_f32 v[44:45], v[44:45], v[168:169]
	v_pk_add_f32 v[38:39], v[38:39], v[170:171]
	v_pk_add_f32 v[40:41], v[40:41], v[172:173]
	v_pk_add_f32 v[34:35], v[34:35], v[174:175]
	v_pk_add_f32 v[36:37], v[36:37], v[176:177]
	global_store_dwordx4 v203, v[46:49], s[24:25]
	global_store_dwordx4 v203, v[42:45], s[24:25] offset:16
	global_store_dwordx4 v203, v[38:41], s[24:25] offset:512
	global_store_dwordx4 v203, v[34:37], s[24:25] offset:528
	s_waitcnt vmcnt(16)
	v_pk_add_f32 v[30:31], v[30:31], v[178:179]
	v_pk_add_f32 v[32:33], v[32:33], v[180:181]
	v_pk_add_f32 v[26:27], v[26:27], v[182:183]
	v_pk_add_f32 v[28:29], v[28:29], v[184:185]
	v_pk_add_f32 v[22:23], v[22:23], v[224:225]
	v_pk_add_f32 v[24:25], v[24:25], v[226:227]
	v_pk_add_f32 v[18:19], v[18:19], v[228:229]
	v_pk_add_f32 v[20:21], v[20:21], v[230:231]
	global_store_dwordx4 v248, v[30:33], s[24:25]
	global_store_dwordx4 v248, v[26:29], s[24:25] offset:16
	global_store_dwordx4 v248, v[22:25], s[24:25] offset:512
	global_store_dwordx4 v248, v[18:21], s[24:25] offset:528
	s_waitcnt vmcnt(12)
	v_pk_add_f32 v[14:15], v[14:15], v[232:233]
	v_pk_add_f32 v[16:17], v[16:17], v[234:235]
	v_pk_add_f32 v[10:11], v[10:11], v[236:237]
	v_pk_add_f32 v[12:13], v[12:13], v[238:239]
	v_pk_add_f32 v[6:7], v[6:7], v[240:241]
	v_pk_add_f32 v[8:9], v[8:9], v[242:243]
	v_pk_add_f32 v[2:3], v[2:3], v[244:245]
	v_pk_add_f32 v[4:5], v[4:5], v[246:247]
	global_store_dwordx4 v249, v[14:17], s[24:25]
	global_store_dwordx4 v249, v[10:13], s[24:25] offset:16
	global_store_dwordx4 v249, v[6:9], s[24:25] offset:512
	global_store_dwordx4 v249, v[2:5], s[24:25] offset:528
	s_cbranch_vccnz .LBB0_1530
	s_andn2_b64 vcc, exec, s[40:41]
	s_cbranch_vccnz .LBB0_1529
	s_barrier
	s_branch .LBB0_1529
